# diff-attention tail: hoist the 16 sub-LN gain loads ahead of the stores, drop 15 per-step vmcnt(0) waits (both copies)
# baseline (speedup 1.0000x reference)
.LBB0_254:
	s_or_b64 exec, exec, s[30:31]
	s_waitcnt lgkmcnt(0)
	s_barrier
	s_and_saveexec_b64 s[30:31], s[0:1]
	s_cbranch_execz .LBB0_256
	ds_read2st64_b32 v[78:79], v64 offset1:1
	ds_read2st64_b32 v[80:81], v64 offset0:2 offset1:3
	ds_read2st64_b32 v[82:83], v64 offset0:4 offset1:5
	ds_read2st64_b32 v[84:85], v64 offset0:6 offset1:7
	ds_read2st64_b32 v[90:91], v64 offset0:8 offset1:9
	ds_read2st64_b32 v[92:93], v64 offset0:10 offset1:11
	ds_read2st64_b32 v[94:95], v64 offset0:12 offset1:13
	ds_read2st64_b32 v[98:99], v64 offset0:14 offset1:15
	ds_read2st64_b32 v[100:101], v64 offset0:16 offset1:17
	ds_read2st64_b32 v[102:103], v64 offset0:18 offset1:19
	ds_read2st64_b32 v[104:105], v64 offset0:20 offset1:21
	ds_read2st64_b32 v[106:107], v64 offset0:22 offset1:23
	ds_read2st64_b32 v[108:109], v64 offset0:24 offset1:25
	ds_read2st64_b32 v[110:111], v64 offset0:26 offset1:27
	ds_read2st64_b32 v[112:113], v64 offset0:28 offset1:29
	s_waitcnt vmcnt(3)
	ds_read2st64_b32 v[114:115], v64 offset0:30 offset1:31
	ds_read2st64_b32 v[116:117], v64 offset0:32 offset1:33
	s_waitcnt vmcnt(2)
	ds_read2st64_b32 v[118:119], v64 offset0:34 offset1:35
	ds_read2st64_b32 v[120:121], v64 offset0:36 offset1:37
	s_waitcnt vmcnt(1)
	ds_read2st64_b32 v[122:123], v64 offset0:38 offset1:39
	ds_read2st64_b32 v[124:125], v64 offset0:40 offset1:41
	s_waitcnt vmcnt(0)
	ds_read2st64_b32 v[126:127], v64 offset0:42 offset1:43
	ds_read2st64_b32 v[88:89], v64 offset0:44 offset1:45
	ds_read2st64_b32 v[128:129], v64 offset0:46 offset1:47
	ds_read2st64_b32 v[76:77], v64 offset0:56 offset1:57
	ds_read2st64_b32 v[86:87], v64 offset0:58 offset1:59
	ds_read2st64_b32 v[66:67], v64 offset0:60 offset1:61
	ds_read2st64_b32 v[72:73], v64 offset0:62 offset1:63
	ds_read2st64_b32 v[130:131], v64 offset0:48 offset1:49
	ds_read2st64_b32 v[132:133], v64 offset0:50 offset1:51
	ds_read2st64_b32 v[134:135], v64 offset0:52 offset1:53
	ds_read2st64_b32 v[136:137], v64 offset0:54 offset1:55
	s_waitcnt lgkmcnt(5)
	v_pk_mul_f32 v[64:65], v[174:175], v[66:67]
	v_pk_mul_f32 v[78:79], v[174:175], v[78:79]
	v_pk_fma_f32 v[64:65], v[12:13], v[68:69], v[64:65] op_sel_hi:[1,0,1] neg_lo:[0,0,1] neg_hi:[0,0,1]
	s_waitcnt lgkmcnt(4)
	v_pk_mul_f32 v[12:13], v[174:175], v[72:73]
	v_readlane_b32 s4, v255, 26
	v_pk_fma_f32 v[66:67], v[14:15], v[68:69], v[12:13] op_sel_hi:[1,0,1] neg_lo:[0,0,1] neg_hi:[0,0,1]
	v_lshrrev_b32_e32 v12, 3, v179
	v_and_b32_e32 v96, 4, v12
	v_lshlrev_b32_e32 v69, 2, v96
	v_pk_fma_f32 v[78:79], v[48:49], v[68:69], v[78:79] op_sel_hi:[1,0,1] neg_lo:[0,0,1] neg_hi:[0,0,1]
	v_pk_mul_f32 v[48:49], v[174:175], v[84:85]
	v_pk_mul_f32 v[12:13], v[174:175], v[80:81]
	v_pk_fma_f32 v[48:49], v[54:55], v[68:69], v[48:49] op_sel_hi:[1,0,1] neg_lo:[0,0,1] neg_hi:[0,0,1]
	v_pk_mul_f32 v[54:55], v[174:175], v[82:83]
	v_pk_fma_f32 v[50:51], v[50:51], v[68:69], v[12:13] op_sel_hi:[1,0,1] neg_lo:[0,0,1] neg_hi:[0,0,1]
	v_pk_fma_f32 v[80:81], v[52:53], v[68:69], v[54:55] op_sel_hi:[1,0,1] neg_lo:[0,0,1] neg_hi:[0,0,1]
	v_pk_mul_f32 v[54:55], v[174:175], v[90:91]
	v_pk_mul_f32 v[52:53], v[174:175], v[92:93]
	v_pk_fma_f32 v[82:83], v[56:57], v[68:69], v[54:55] op_sel_hi:[1,0,1] neg_lo:[0,0,1] neg_hi:[0,0,1]
	v_pk_mul_f32 v[56:57], v[174:175], v[94:95]
	v_pk_fma_f32 v[52:53], v[58:59], v[68:69], v[52:53] op_sel_hi:[1,0,1] neg_lo:[0,0,1] neg_hi:[0,0,1]
	v_pk_fma_f32 v[84:85], v[60:61], v[68:69], v[56:57] op_sel_hi:[1,0,1] neg_lo:[0,0,1] neg_hi:[0,0,1]
	v_pk_mul_f32 v[56:57], v[174:175], v[102:103]
	v_pk_mul_f32 v[54:55], v[174:175], v[98:99]
	v_pk_fma_f32 v[56:57], v[34:35], v[68:69], v[56:57] op_sel_hi:[1,0,1] neg_lo:[0,0,1] neg_hi:[0,0,1]
	v_pk_mul_f32 v[34:35], v[174:175], v[100:101]
	v_pk_fma_f32 v[54:55], v[62:63], v[68:69], v[54:55] op_sel_hi:[1,0,1] neg_lo:[0,0,1] neg_hi:[0,0,1]
	v_pk_fma_f32 v[58:59], v[32:33], v[68:69], v[34:35] op_sel_hi:[1,0,1] neg_lo:[0,0,1] neg_hi:[0,0,1]
	v_pk_mul_f32 v[32:33], v[174:175], v[106:107]
	v_pk_mul_f32 v[34:35], v[174:175], v[104:105]
	v_pk_fma_f32 v[32:33], v[38:39], v[68:69], v[32:33] op_sel_hi:[1,0,1] neg_lo:[0,0,1] neg_hi:[0,0,1]
	v_pk_mul_f32 v[38:39], v[174:175], v[112:113]
	v_pk_fma_f32 v[60:61], v[36:37], v[68:69], v[34:35] op_sel_hi:[1,0,1] neg_lo:[0,0,1] neg_hi:[0,0,1]
	v_pk_fma_f32 v[44:45], v[44:45], v[68:69], v[38:39] op_sel_hi:[1,0,1] neg_lo:[0,0,1] neg_hi:[0,0,1]
	v_pk_mul_f32 v[38:39], v[174:175], v[118:119]
	v_pk_mul_f32 v[36:37], v[174:175], v[108:109]
	v_pk_fma_f32 v[38:39], v[18:19], v[68:69], v[38:39] op_sel_hi:[1,0,1] neg_lo:[0,0,1] neg_hi:[0,0,1]
	v_pk_mul_f32 v[18:19], v[174:175], v[116:117]
	v_pk_fma_f32 v[62:63], v[40:41], v[68:69], v[36:37] op_sel_hi:[1,0,1] neg_lo:[0,0,1] neg_hi:[0,0,1]
	v_pk_fma_f32 v[40:41], v[16:17], v[68:69], v[18:19] op_sel_hi:[1,0,1] neg_lo:[0,0,1] neg_hi:[0,0,1]
	v_pk_mul_f32 v[16:17], v[174:175], v[122:123]
	v_pk_mul_f32 v[34:35], v[174:175], v[110:111]
	v_pk_fma_f32 v[16:17], v[22:23], v[68:69], v[16:17] op_sel_hi:[1,0,1] neg_lo:[0,0,1] neg_hi:[0,0,1]
	v_pk_mul_f32 v[22:23], v[174:175], v[88:89]
	v_pk_mul_f32 v[18:19], v[174:175], v[120:121]
	v_pk_fma_f32 v[28:29], v[28:29], v[68:69], v[22:23] op_sel_hi:[1,0,1] neg_lo:[0,0,1] neg_hi:[0,0,1]
	s_waitcnt lgkmcnt(2)
	v_pk_mul_f32 v[22:23], v[174:175], v[132:133]
	v_pk_fma_f32 v[34:35], v[42:43], v[68:69], v[34:35] op_sel_hi:[1,0,1] neg_lo:[0,0,1] neg_hi:[0,0,1]
	v_pk_fma_f32 v[42:43], v[20:21], v[68:69], v[18:19] op_sel_hi:[1,0,1] neg_lo:[0,0,1] neg_hi:[0,0,1]
	v_pk_mul_f32 v[18:19], v[174:175], v[126:127]
	v_pk_mul_f32 v[20:21], v[174:175], v[124:125]
	v_pk_fma_f32 v[22:23], v[2:3], v[68:69], v[22:23] op_sel_hi:[1,0,1] neg_lo:[0,0,1] neg_hi:[0,0,1]
	v_pk_mul_f32 v[2:3], v[174:175], v[130:131]
	v_pk_fma_f32 v[18:19], v[26:27], v[68:69], v[18:19] op_sel_hi:[1,0,1] neg_lo:[0,0,1] neg_hi:[0,0,1]
	v_pk_fma_f32 v[26:27], v[24:25], v[68:69], v[20:21] op_sel_hi:[1,0,1] neg_lo:[0,0,1] neg_hi:[0,0,1]
	v_pk_fma_f32 v[24:25], v[0:1], v[68:69], v[2:3] op_sel_hi:[1,0,1] neg_lo:[0,0,1] neg_hi:[0,0,1]
	s_waitcnt lgkmcnt(0)
	v_pk_mul_f32 v[0:1], v[174:175], v[136:137]
	v_pk_mul_f32 v[2:3], v[174:175], v[134:135]
	v_readlane_b32 s10, v255, 32
	v_readlane_b32 s11, v255, 33
	v_pk_mul_f32 v[140:141], v[78:79], v[78:79]
	v_pk_mul_f32 v[36:37], v[174:175], v[114:115]
	v_pk_mul_f32 v[20:21], v[174:175], v[128:129]
	v_pk_fma_f32 v[0:1], v[6:7], v[68:69], v[0:1] op_sel_hi:[1,0,1] neg_lo:[0,0,1] neg_hi:[0,0,1]
	v_pk_fma_f32 v[4:5], v[4:5], v[68:69], v[2:3] op_sel_hi:[1,0,1] neg_lo:[0,0,1] neg_hi:[0,0,1]
	v_pk_mul_f32 v[2:3], v[174:175], v[86:87]
	v_pk_mul_f32 v[6:7], v[174:175], v[76:77]
	v_pk_mul_f32 v[138:139], v[50:51], v[50:51]
	global_load_dwordx4 v[12:15], v69, s[10:11]
	v_pk_fma_f32 v[36:37], v[46:47], v[68:69], v[36:37] op_sel_hi:[1,0,1] neg_lo:[0,0,1] neg_hi:[0,0,1]
	v_pk_fma_f32 v[20:21], v[30:31], v[68:69], v[20:21] op_sel_hi:[1,0,1] neg_lo:[0,0,1] neg_hi:[0,0,1]
	v_pk_fma_f32 v[2:3], v[10:11], v[68:69], v[2:3] op_sel_hi:[1,0,1] neg_lo:[0,0,1] neg_hi:[0,0,1]
	v_pk_fma_f32 v[6:7], v[8:9], v[68:69], v[6:7] op_sel_hi:[1,0,1] neg_lo:[0,0,1] neg_hi:[0,0,1]
	v_add_f32_e32 v68, v140, v141
	v_add_f32_e32 v68, v68, v138
	v_pk_mul_f32 v[144:145], v[80:81], v[80:81]
	v_add_f32_e32 v68, v68, v139
	v_add_f32_e32 v68, v68, v144
	v_pk_mul_f32 v[142:143], v[48:49], v[48:49]
	v_add_f32_e32 v68, v68, v145
	v_add_f32_e32 v68, v68, v142
	v_pk_mul_f32 v[90:91], v[82:83], v[82:83]
	v_add_f32_e32 v68, v68, v143
	v_add_f32_e32 v68, v68, v90
	v_pk_mul_f32 v[92:93], v[52:53], v[52:53]
	v_add_f32_e32 v68, v68, v91
	v_add_f32_e32 v68, v68, v92
	v_pk_mul_f32 v[94:95], v[84:85], v[84:85]
	v_add_f32_e32 v68, v68, v93
	v_add_f32_e32 v68, v68, v94
	v_pk_mul_f32 v[98:99], v[54:55], v[54:55]
	v_add_f32_e32 v68, v68, v95
	v_add_f32_e32 v68, v68, v98
	v_pk_mul_f32 v[100:101], v[58:59], v[58:59]
	v_add_f32_e32 v68, v68, v99
	v_add_f32_e32 v68, v68, v100
	v_pk_mul_f32 v[102:103], v[56:57], v[56:57]
	v_add_f32_e32 v68, v68, v101
	v_add_f32_e32 v68, v68, v102
	v_pk_mul_f32 v[104:105], v[60:61], v[60:61]
	v_add_f32_e32 v68, v68, v103
	v_add_f32_e32 v68, v68, v104
	v_pk_mul_f32 v[106:107], v[32:33], v[32:33]
	v_add_f32_e32 v68, v68, v105
	v_add_f32_e32 v68, v68, v106
	v_pk_mul_f32 v[108:109], v[62:63], v[62:63]
	v_add_f32_e32 v68, v68, v107
	v_add_f32_e32 v68, v68, v108
	v_pk_mul_f32 v[110:111], v[34:35], v[34:35]
	v_add_f32_e32 v68, v68, v109
	v_add_f32_e32 v68, v68, v110
	v_pk_mul_f32 v[112:113], v[44:45], v[44:45]
	v_add_f32_e32 v68, v68, v111
	v_add_f32_e32 v68, v68, v112
	v_pk_mul_f32 v[46:47], v[36:37], v[36:37]
	v_add_f32_e32 v68, v68, v113
	v_add_f32_e32 v46, v68, v46
	v_pk_mul_f32 v[116:117], v[40:41], v[40:41]
	v_add_f32_e32 v46, v46, v47
	v_add_f32_e32 v46, v46, v116
	v_pk_mul_f32 v[114:115], v[38:39], v[38:39]
	v_add_f32_e32 v46, v46, v117
	v_add_f32_e32 v46, v46, v114
	v_pk_mul_f32 v[120:121], v[42:43], v[42:43]
	v_add_f32_e32 v46, v46, v115
	v_add_f32_e32 v46, v46, v120
	v_pk_mul_f32 v[118:119], v[16:17], v[16:17]
	v_add_f32_e32 v46, v46, v121
	v_add_f32_e32 v46, v46, v118
	v_pk_mul_f32 v[124:125], v[26:27], v[26:27]
	v_add_f32_e32 v46, v46, v119
	v_add_f32_e32 v46, v46, v124
	v_pk_mul_f32 v[122:123], v[18:19], v[18:19]
	v_add_f32_e32 v46, v46, v125
	v_add_f32_e32 v46, v46, v122
	v_pk_mul_f32 v[88:89], v[28:29], v[28:29]
	v_add_f32_e32 v46, v46, v123
	v_add_f32_e32 v46, v46, v88
	v_pk_mul_f32 v[30:31], v[20:21], v[20:21]
	v_add_f32_e32 v46, v46, v89
	v_add_f32_e32 v30, v46, v30
	v_pk_mul_f32 v[128:129], v[24:25], v[24:25]
	v_add_f32_e32 v30, v30, v31
	v_add_f32_e32 v30, v30, v128
	v_pk_mul_f32 v[126:127], v[22:23], v[22:23]
	v_add_f32_e32 v30, v30, v129
	v_add_f32_e32 v30, v30, v126
	v_pk_mul_f32 v[132:133], v[4:5], v[4:5]
	v_add_f32_e32 v30, v30, v127
	v_add_f32_e32 v30, v30, v132
	v_pk_mul_f32 v[130:131], v[0:1], v[0:1]
	v_add_f32_e32 v30, v30, v133
	v_add_f32_e32 v30, v30, v130
	v_pk_mul_f32 v[8:9], v[6:7], v[6:7]
	v_add_f32_e32 v30, v30, v131
	v_add_f32_e32 v8, v30, v8
	v_pk_mul_f32 v[10:11], v[2:3], v[2:3]
	v_add_f32_e32 v8, v8, v9
	v_add_f32_e32 v8, v8, v10
	v_pk_mul_f32 v[70:71], v[64:65], v[64:65]
	v_add_f32_e32 v8, v8, v11
	v_add_f32_e32 v8, v8, v70
	v_pk_mul_f32 v[72:73], v[66:67], v[66:67]
	v_add_f32_e32 v8, v8, v71
	v_add_f32_e32 v8, v8, v72
	v_add_f32_e32 v10, v8, v73
	ds_bpermute_b32 v11, v171, v10
	global_load_dwordx4 v[122:125], v69, s[10:11] offset:32
	global_load_dwordx4 v[126:129], v69, s[10:11] offset:64
	global_load_dwordx4 v[130:133], v69, s[10:11] offset:96
	global_load_dwordx4 v[134:137], v69, s[10:11] offset:128
	global_load_dwordx4 v[138:141], v69, s[10:11] offset:160
	global_load_dwordx4 v[142:145], v69, s[10:11] offset:192
	global_load_dwordx4 v[146:149], v69, s[10:11] offset:224
	global_load_dwordx4 v[150:153], v69, s[10:11] offset:256
	global_load_dwordx4 v[180:183], v69, s[10:11] offset:288
	global_load_dwordx4 v[184:187], v69, s[10:11] offset:320
	global_load_dwordx4 v[188:191], v69, s[10:11] offset:352
	global_load_dwordx4 v[192:195], v69, s[10:11] offset:384
	global_load_dwordx4 v[196:199], v69, s[10:11] offset:416
	global_load_dwordx4 v[200:203], v69, s[10:11] offset:448
	global_load_dwordx4 v[216:219], v69, s[10:11] offset:480
	s_lshl_b32 s24, s37, 8
	v_ashrrev_i32_e32 v177, 31, v176
	v_lshl_add_u64 v[74:75], v[176:177], 0, s[24:25]
	v_and_or_b32 v74, v179, 31, v74
	s_waitcnt lgkmcnt(0)
	v_add_f32_e32 v10, v10, v11
	v_fmamk_f32 v10, v10, 0x3c000000, v248
	v_mul_f32_e32 v11, 0x4b800000, v10
	v_cmp_gt_f32_e32 vcc, s82, v10
	v_lshlrev_b64 v[8:9], 11, v[74:75]
	v_lshl_add_u64 v[8:9], s[92:93], 0, v[8:9]
	v_cndmask_b32_e32 v10, v10, v11, vcc
	v_rsq_f32_e32 v10, v10
	s_lshl_b32 s24, s36, 1
	v_lshl_add_u64 v[8:9], v[8:9], 0, s[24:25]
	v_lshlrev_b32_e32 v96, 1, v96
	v_lshl_add_u64 v[30:31], v[8:9], 0, v[96:97]
	v_mul_f32_e32 v8, 0x45800000, v10
	v_cndmask_b32_e32 v8, v10, v8, vcc
	v_mul_f32_e32 v46, 0x3f4ccccd, v8
	v_pk_mul_f32 v[8:9], v[78:79], v[46:47] op_sel_hi:[1,0]
	v_pk_mul_f32 v[10:11], v[50:51], v[46:47] op_sel_hi:[1,0]
	s_waitcnt vmcnt(0)
	v_pk_mul_f32 v[8:9], v[12:13], v[8:9]
	v_pk_mul_f32 v[10:11], v[14:15], v[10:11]
	v_cvt_pk_bf16_f32 v8, v8, v9
	v_cvt_pk_bf16_f32 v9, v10, v11
	v_add_co_u32_e32 v10, vcc, s33, v30
	v_pk_mul_f32 v[14:15], v[80:81], v[46:47] op_sel_hi:[1,0]
	s_nop 0
	v_addc_co_u32_e32 v11, vcc, 0, v31, vcc
	global_store_dwordx2 v[10:11], v[8:9], off offset:1024
	s_mov_b64 s[0:1], 0x11d00400
	v_lshl_add_u64 v[12:13], v[30:31], 0, s[0:1]
	v_pk_mul_f32 v[30:31], v[52:53], v[46:47] op_sel_hi:[1,0]
	v_pk_mul_f32 v[16:17], v[16:17], v[46:47] op_sel_hi:[1,0]
	v_pk_mul_f32 v[4:5], v[4:5], v[46:47] op_sel_hi:[1,0]
	v_pk_mul_f32 v[0:1], v[0:1], v[46:47] op_sel_hi:[1,0]
	v_pk_mul_f32 v[2:3], v[2:3], v[46:47] op_sel_hi:[1,0]
	v_readlane_b32 s5, v255, 27
	v_readlane_b32 s6, v255, 28
	s_mov_b32 s6, s78
	s_mov_b32 s5, s72
	v_readlane_b32 s7, v255, 29
	v_readlane_b32 s8, v255, 30
	v_readlane_b32 s9, v255, 31
	v_readlane_b32 s12, v255, 34
	v_readlane_b32 s13, v255, 35
	v_readlane_b32 s14, v255, 36
	v_readlane_b32 s15, v255, 37
	v_readlane_b32 s16, v255, 38
	v_readlane_b32 s17, v255, 39
	v_readlane_b32 s18, v255, 40
	v_readlane_b32 s19, v255, 41
	v_pk_mul_f32 v[122:123], v[122:123], v[14:15]
	v_pk_mul_f32 v[14:15], v[48:49], v[46:47] op_sel_hi:[1,0]
	v_cvt_pk_bf16_f32 v122, v122, v123
	v_pk_mul_f32 v[124:125], v[124:125], v[14:15]
	v_pk_mul_f32 v[14:15], v[82:83], v[46:47] op_sel_hi:[1,0]
	v_cvt_pk_bf16_f32 v123, v124, v125
	global_store_dwordx2 v[12:13], v[122:123], off offset:16
	v_pk_mul_f32 v[126:127], v[126:127], v[14:15]
	v_pk_mul_f32 v[128:129], v[128:129], v[30:31]
	v_cvt_pk_bf16_f32 v126, v126, v127
	v_cvt_pk_bf16_f32 v127, v128, v129
	global_store_dwordx2 v[12:13], v[126:127], off offset:32
	v_pk_mul_f32 v[14:15], v[84:85], v[46:47] op_sel_hi:[1,0]
	v_pk_mul_f32 v[30:31], v[54:55], v[46:47] op_sel_hi:[1,0]
	v_pk_mul_f32 v[130:131], v[14:15], v[130:131]
	v_pk_mul_f32 v[132:133], v[30:31], v[132:133]
	v_cvt_pk_bf16_f32 v130, v130, v131
	v_cvt_pk_bf16_f32 v131, v132, v133
	global_store_dwordx2 v[12:13], v[130:131], off offset:48
	v_pk_mul_f32 v[14:15], v[58:59], v[46:47] op_sel_hi:[1,0]
	v_pk_mul_f32 v[30:31], v[56:57], v[46:47] op_sel_hi:[1,0]
	v_pk_mul_f32 v[134:135], v[14:15], v[134:135]
	v_pk_mul_f32 v[136:137], v[30:31], v[136:137]
	v_cvt_pk_bf16_f32 v134, v134, v135
	v_cvt_pk_bf16_f32 v135, v136, v137
	global_store_dwordx2 v[12:13], v[134:135], off offset:64
	v_pk_mul_f32 v[14:15], v[60:61], v[46:47] op_sel_hi:[1,0]
	v_pk_mul_f32 v[30:31], v[32:33], v[46:47] op_sel_hi:[1,0]
	v_pk_mul_f32 v[138:139], v[14:15], v[138:139]
	v_pk_mul_f32 v[140:141], v[30:31], v[140:141]
	v_cvt_pk_bf16_f32 v138, v138, v139
	v_cvt_pk_bf16_f32 v139, v140, v141
	global_store_dwordx2 v[12:13], v[138:139], off offset:80
	v_pk_mul_f32 v[14:15], v[62:63], v[46:47] op_sel_hi:[1,0]
	v_pk_mul_f32 v[30:31], v[34:35], v[46:47] op_sel_hi:[1,0]
	v_pk_mul_f32 v[142:143], v[14:15], v[142:143]
	v_pk_mul_f32 v[144:145], v[30:31], v[144:145]
	v_cvt_pk_bf16_f32 v142, v142, v143
	v_cvt_pk_bf16_f32 v143, v144, v145
	global_store_dwordx2 v[12:13], v[142:143], off offset:96
	v_pk_mul_f32 v[14:15], v[44:45], v[46:47] op_sel_hi:[1,0]
	v_pk_mul_f32 v[30:31], v[36:37], v[46:47] op_sel_hi:[1,0]
	v_pk_mul_f32 v[146:147], v[14:15], v[146:147]
	v_pk_mul_f32 v[148:149], v[30:31], v[148:149]
	v_cvt_pk_bf16_f32 v146, v146, v147
	v_cvt_pk_bf16_f32 v147, v148, v149
	global_store_dwordx2 v[12:13], v[146:147], off offset:112
	v_pk_mul_f32 v[14:15], v[40:41], v[46:47] op_sel_hi:[1,0]
	v_pk_mul_f32 v[30:31], v[38:39], v[46:47] op_sel_hi:[1,0]
	v_pk_mul_f32 v[150:151], v[14:15], v[150:151]
	v_pk_mul_f32 v[152:153], v[30:31], v[152:153]
	v_cvt_pk_bf16_f32 v150, v150, v151
	v_cvt_pk_bf16_f32 v151, v152, v153
	global_store_dwordx2 v[12:13], v[150:151], off offset:128
	v_pk_mul_f32 v[14:15], v[42:43], v[46:47] op_sel_hi:[1,0]
	v_pk_mul_f32 v[182:183], v[16:17], v[182:183]
	v_pk_mul_f32 v[180:181], v[14:15], v[180:181]
	v_pk_mul_f32 v[14:15], v[26:27], v[46:47] op_sel_hi:[1,0]
	v_cvt_pk_bf16_f32 v180, v180, v181
	v_cvt_pk_bf16_f32 v181, v182, v183
	global_store_dwordx2 v[12:13], v[180:181], off offset:144
	v_pk_mul_f32 v[16:17], v[18:19], v[46:47] op_sel_hi:[1,0]
	v_pk_mul_f32 v[184:185], v[14:15], v[184:185]
	v_pk_mul_f32 v[186:187], v[16:17], v[186:187]
	v_cvt_pk_bf16_f32 v184, v184, v185
	v_cvt_pk_bf16_f32 v185, v186, v187
	global_store_dwordx2 v[12:13], v[184:185], off offset:160
	v_pk_mul_f32 v[14:15], v[28:29], v[46:47] op_sel_hi:[1,0]
	v_pk_mul_f32 v[16:17], v[20:21], v[46:47] op_sel_hi:[1,0]
	v_pk_mul_f32 v[188:189], v[14:15], v[188:189]
	v_pk_mul_f32 v[190:191], v[16:17], v[190:191]
	v_cvt_pk_bf16_f32 v188, v188, v189
	v_cvt_pk_bf16_f32 v189, v190, v191
	global_store_dwordx2 v[12:13], v[188:189], off offset:176
	v_pk_mul_f32 v[14:15], v[24:25], v[46:47] op_sel_hi:[1,0]
	v_pk_mul_f32 v[16:17], v[22:23], v[46:47] op_sel_hi:[1,0]
	v_pk_mul_f32 v[192:193], v[14:15], v[192:193]
	v_pk_mul_f32 v[194:195], v[16:17], v[194:195]
	v_cvt_pk_bf16_f32 v192, v192, v193
	v_cvt_pk_bf16_f32 v193, v194, v195
	global_store_dwordx2 v[12:13], v[192:193], off offset:192
	v_pk_mul_f32 v[4:5], v[4:5], v[196:197]
	v_pk_mul_f32 v[0:1], v[0:1], v[198:199]
	v_cvt_pk_bf16_f32 v4, v4, v5
	v_cvt_pk_bf16_f32 v5, v0, v1
	global_store_dwordx2 v[12:13], v[4:5], off offset:208
	v_pk_mul_f32 v[0:1], v[6:7], v[46:47] op_sel_hi:[1,0]
	v_pk_mul_f32 v[4:5], v[64:65], v[46:47] op_sel_hi:[1,0]
	v_pk_mul_f32 v[6:7], v[66:67], v[46:47] op_sel_hi:[1,0]
	v_pk_mul_f32 v[0:1], v[0:1], v[200:201]
	v_pk_mul_f32 v[2:3], v[2:3], v[202:203]
	v_cvt_pk_bf16_f32 v0, v0, v1
	v_cvt_pk_bf16_f32 v1, v2, v3
	global_store_dwordx2 v[12:13], v[0:1], off offset:224
	v_pk_mul_f32 v[216:217], v[4:5], v[216:217]
	v_pk_mul_f32 v[218:219], v[6:7], v[218:219]
	v_cvt_pk_bf16_f32 v216, v216, v217
	v_cvt_pk_bf16_f32 v217, v218, v219
	global_store_dwordx2 v[12:13], v[216:217], off offset:240

.LBB0_298:
	s_or_b64 exec, exec, s[30:31]
	s_waitcnt lgkmcnt(0)
	s_barrier
	s_and_saveexec_b64 s[30:31], s[0:1]
	s_cbranch_execz .LBB0_300
	ds_read2st64_b32 v[76:77], v64 offset1:1
	ds_read2st64_b32 v[80:81], v64 offset0:2 offset1:3
	ds_read2st64_b32 v[82:83], v64 offset0:4 offset1:5
	ds_read2st64_b32 v[84:85], v64 offset0:6 offset1:7
	ds_read2st64_b32 v[90:91], v64 offset0:8 offset1:9
	ds_read2st64_b32 v[92:93], v64 offset0:10 offset1:11
	ds_read2st64_b32 v[94:95], v64 offset0:12 offset1:13
	ds_read2st64_b32 v[98:99], v64 offset0:14 offset1:15
	ds_read2st64_b32 v[100:101], v64 offset0:16 offset1:17
	ds_read2st64_b32 v[102:103], v64 offset0:18 offset1:19
	ds_read2st64_b32 v[104:105], v64 offset0:20 offset1:21
	ds_read2st64_b32 v[106:107], v64 offset0:22 offset1:23
	ds_read2st64_b32 v[108:109], v64 offset0:24 offset1:25
	ds_read2st64_b32 v[110:111], v64 offset0:26 offset1:27
	ds_read2st64_b32 v[112:113], v64 offset0:28 offset1:29
	s_waitcnt vmcnt(3)
	ds_read2st64_b32 v[114:115], v64 offset0:30 offset1:31
	ds_read2st64_b32 v[116:117], v64 offset0:32 offset1:33
	s_waitcnt vmcnt(2)
	ds_read2st64_b32 v[118:119], v64 offset0:34 offset1:35
	ds_read2st64_b32 v[120:121], v64 offset0:36 offset1:37
	s_waitcnt vmcnt(1)
	ds_read2st64_b32 v[122:123], v64 offset0:38 offset1:39
	ds_read2st64_b32 v[124:125], v64 offset0:40 offset1:41
	s_waitcnt vmcnt(0)
	ds_read2st64_b32 v[126:127], v64 offset0:42 offset1:43
	ds_read2st64_b32 v[88:89], v64 offset0:44 offset1:45
	ds_read2st64_b32 v[128:129], v64 offset0:46 offset1:47
	ds_read2st64_b32 v[78:79], v64 offset0:56 offset1:57
	ds_read2st64_b32 v[86:87], v64 offset0:58 offset1:59
	ds_read2st64_b32 v[66:67], v64 offset0:60 offset1:61
	ds_read2st64_b32 v[72:73], v64 offset0:62 offset1:63
	ds_read2st64_b32 v[130:131], v64 offset0:48 offset1:49
	ds_read2st64_b32 v[132:133], v64 offset0:50 offset1:51
	ds_read2st64_b32 v[134:135], v64 offset0:52 offset1:53
	ds_read2st64_b32 v[136:137], v64 offset0:54 offset1:55
	s_waitcnt lgkmcnt(5)
	v_pk_mul_f32 v[64:65], v[174:175], v[66:67]
	v_pk_mul_f32 v[76:77], v[174:175], v[76:77]
	v_pk_fma_f32 v[64:65], v[12:13], v[68:69], v[64:65] op_sel_hi:[1,0,1] neg_lo:[0,0,1] neg_hi:[0,0,1]
	s_waitcnt lgkmcnt(4)
	v_pk_mul_f32 v[12:13], v[174:175], v[72:73]
	v_readlane_b32 s4, v255, 26
	v_pk_fma_f32 v[66:67], v[14:15], v[68:69], v[12:13] op_sel_hi:[1,0,1] neg_lo:[0,0,1] neg_hi:[0,0,1]
	v_lshrrev_b32_e32 v12, 3, v179
	v_and_b32_e32 v96, 4, v12
	v_lshlrev_b32_e32 v69, 2, v96
	v_pk_fma_f32 v[76:77], v[48:49], v[68:69], v[76:77] op_sel_hi:[1,0,1] neg_lo:[0,0,1] neg_hi:[0,0,1]
	v_pk_mul_f32 v[48:49], v[174:175], v[84:85]
	v_pk_mul_f32 v[12:13], v[174:175], v[80:81]
	v_pk_fma_f32 v[48:49], v[54:55], v[68:69], v[48:49] op_sel_hi:[1,0,1] neg_lo:[0,0,1] neg_hi:[0,0,1]
	v_pk_mul_f32 v[54:55], v[174:175], v[82:83]
	v_pk_fma_f32 v[50:51], v[50:51], v[68:69], v[12:13] op_sel_hi:[1,0,1] neg_lo:[0,0,1] neg_hi:[0,0,1]
	v_pk_fma_f32 v[80:81], v[52:53], v[68:69], v[54:55] op_sel_hi:[1,0,1] neg_lo:[0,0,1] neg_hi:[0,0,1]
	v_pk_mul_f32 v[54:55], v[174:175], v[90:91]
	v_pk_mul_f32 v[52:53], v[174:175], v[92:93]
	v_pk_fma_f32 v[82:83], v[56:57], v[68:69], v[54:55] op_sel_hi:[1,0,1] neg_lo:[0,0,1] neg_hi:[0,0,1]
	v_pk_mul_f32 v[56:57], v[174:175], v[94:95]
	v_pk_fma_f32 v[52:53], v[58:59], v[68:69], v[52:53] op_sel_hi:[1,0,1] neg_lo:[0,0,1] neg_hi:[0,0,1]
	v_pk_fma_f32 v[84:85], v[60:61], v[68:69], v[56:57] op_sel_hi:[1,0,1] neg_lo:[0,0,1] neg_hi:[0,0,1]
	v_pk_mul_f32 v[56:57], v[174:175], v[102:103]
	v_pk_mul_f32 v[54:55], v[174:175], v[98:99]
	v_pk_fma_f32 v[56:57], v[34:35], v[68:69], v[56:57] op_sel_hi:[1,0,1] neg_lo:[0,0,1] neg_hi:[0,0,1]
	v_pk_mul_f32 v[34:35], v[174:175], v[100:101]
	v_pk_fma_f32 v[54:55], v[62:63], v[68:69], v[54:55] op_sel_hi:[1,0,1] neg_lo:[0,0,1] neg_hi:[0,0,1]
	v_pk_fma_f32 v[58:59], v[32:33], v[68:69], v[34:35] op_sel_hi:[1,0,1] neg_lo:[0,0,1] neg_hi:[0,0,1]
	v_pk_mul_f32 v[32:33], v[174:175], v[106:107]
	v_pk_mul_f32 v[34:35], v[174:175], v[104:105]
	v_pk_fma_f32 v[32:33], v[38:39], v[68:69], v[32:33] op_sel_hi:[1,0,1] neg_lo:[0,0,1] neg_hi:[0,0,1]
	v_pk_mul_f32 v[38:39], v[174:175], v[112:113]
	v_pk_fma_f32 v[60:61], v[36:37], v[68:69], v[34:35] op_sel_hi:[1,0,1] neg_lo:[0,0,1] neg_hi:[0,0,1]
	v_pk_fma_f32 v[44:45], v[44:45], v[68:69], v[38:39] op_sel_hi:[1,0,1] neg_lo:[0,0,1] neg_hi:[0,0,1]
	v_pk_mul_f32 v[38:39], v[174:175], v[118:119]
	v_pk_mul_f32 v[36:37], v[174:175], v[108:109]
	v_pk_fma_f32 v[38:39], v[18:19], v[68:69], v[38:39] op_sel_hi:[1,0,1] neg_lo:[0,0,1] neg_hi:[0,0,1]
	v_pk_mul_f32 v[18:19], v[174:175], v[116:117]
	v_pk_fma_f32 v[62:63], v[40:41], v[68:69], v[36:37] op_sel_hi:[1,0,1] neg_lo:[0,0,1] neg_hi:[0,0,1]
	v_pk_fma_f32 v[40:41], v[16:17], v[68:69], v[18:19] op_sel_hi:[1,0,1] neg_lo:[0,0,1] neg_hi:[0,0,1]
	v_pk_mul_f32 v[16:17], v[174:175], v[122:123]
	v_pk_mul_f32 v[34:35], v[174:175], v[110:111]
	v_pk_fma_f32 v[16:17], v[22:23], v[68:69], v[16:17] op_sel_hi:[1,0,1] neg_lo:[0,0,1] neg_hi:[0,0,1]
	v_pk_mul_f32 v[22:23], v[174:175], v[88:89]
	v_pk_mul_f32 v[18:19], v[174:175], v[120:121]
	v_pk_fma_f32 v[28:29], v[28:29], v[68:69], v[22:23] op_sel_hi:[1,0,1] neg_lo:[0,0,1] neg_hi:[0,0,1]
	s_waitcnt lgkmcnt(2)
	v_pk_mul_f32 v[22:23], v[174:175], v[132:133]
	v_pk_fma_f32 v[34:35], v[42:43], v[68:69], v[34:35] op_sel_hi:[1,0,1] neg_lo:[0,0,1] neg_hi:[0,0,1]
	v_pk_fma_f32 v[42:43], v[20:21], v[68:69], v[18:19] op_sel_hi:[1,0,1] neg_lo:[0,0,1] neg_hi:[0,0,1]
	v_pk_mul_f32 v[18:19], v[174:175], v[126:127]
	v_pk_mul_f32 v[20:21], v[174:175], v[124:125]
	v_pk_fma_f32 v[22:23], v[2:3], v[68:69], v[22:23] op_sel_hi:[1,0,1] neg_lo:[0,0,1] neg_hi:[0,0,1]
	v_pk_mul_f32 v[2:3], v[174:175], v[130:131]
	v_pk_fma_f32 v[18:19], v[26:27], v[68:69], v[18:19] op_sel_hi:[1,0,1] neg_lo:[0,0,1] neg_hi:[0,0,1]
	v_pk_fma_f32 v[26:27], v[24:25], v[68:69], v[20:21] op_sel_hi:[1,0,1] neg_lo:[0,0,1] neg_hi:[0,0,1]
	v_pk_fma_f32 v[24:25], v[0:1], v[68:69], v[2:3] op_sel_hi:[1,0,1] neg_lo:[0,0,1] neg_hi:[0,0,1]
	s_waitcnt lgkmcnt(0)
	v_pk_mul_f32 v[0:1], v[174:175], v[136:137]
	v_pk_mul_f32 v[2:3], v[174:175], v[134:135]
	v_readlane_b32 s10, v255, 32
	v_readlane_b32 s11, v255, 33
	v_pk_mul_f32 v[140:141], v[76:77], v[76:77]
	v_pk_mul_f32 v[36:37], v[174:175], v[114:115]
	v_pk_mul_f32 v[20:21], v[174:175], v[128:129]
	v_pk_fma_f32 v[0:1], v[6:7], v[68:69], v[0:1] op_sel_hi:[1,0,1] neg_lo:[0,0,1] neg_hi:[0,0,1]
	v_pk_fma_f32 v[4:5], v[4:5], v[68:69], v[2:3] op_sel_hi:[1,0,1] neg_lo:[0,0,1] neg_hi:[0,0,1]
	v_pk_mul_f32 v[2:3], v[174:175], v[86:87]
	v_pk_mul_f32 v[6:7], v[174:175], v[78:79]
	v_pk_mul_f32 v[138:139], v[50:51], v[50:51]
	global_load_dwordx4 v[12:15], v69, s[10:11]
	v_pk_fma_f32 v[36:37], v[46:47], v[68:69], v[36:37] op_sel_hi:[1,0,1] neg_lo:[0,0,1] neg_hi:[0,0,1]
	v_pk_fma_f32 v[20:21], v[30:31], v[68:69], v[20:21] op_sel_hi:[1,0,1] neg_lo:[0,0,1] neg_hi:[0,0,1]
	v_pk_fma_f32 v[2:3], v[10:11], v[68:69], v[2:3] op_sel_hi:[1,0,1] neg_lo:[0,0,1] neg_hi:[0,0,1]
	v_pk_fma_f32 v[6:7], v[8:9], v[68:69], v[6:7] op_sel_hi:[1,0,1] neg_lo:[0,0,1] neg_hi:[0,0,1]
	v_add_f32_e32 v68, v140, v141
	v_add_f32_e32 v68, v68, v138
	v_pk_mul_f32 v[144:145], v[80:81], v[80:81]
	v_add_f32_e32 v68, v68, v139
	v_add_f32_e32 v68, v68, v144
	v_pk_mul_f32 v[142:143], v[48:49], v[48:49]
	v_add_f32_e32 v68, v68, v145
	v_add_f32_e32 v68, v68, v142
	v_pk_mul_f32 v[90:91], v[82:83], v[82:83]
	v_add_f32_e32 v68, v68, v143
	v_add_f32_e32 v68, v68, v90
	v_pk_mul_f32 v[92:93], v[52:53], v[52:53]
	v_add_f32_e32 v68, v68, v91
	v_add_f32_e32 v68, v68, v92
	v_pk_mul_f32 v[94:95], v[84:85], v[84:85]
	v_add_f32_e32 v68, v68, v93
	v_add_f32_e32 v68, v68, v94
	v_pk_mul_f32 v[98:99], v[54:55], v[54:55]
	v_add_f32_e32 v68, v68, v95
	v_add_f32_e32 v68, v68, v98
	v_pk_mul_f32 v[100:101], v[58:59], v[58:59]
	v_add_f32_e32 v68, v68, v99
	v_add_f32_e32 v68, v68, v100
	v_pk_mul_f32 v[102:103], v[56:57], v[56:57]
	v_add_f32_e32 v68, v68, v101
	v_add_f32_e32 v68, v68, v102
	v_pk_mul_f32 v[104:105], v[60:61], v[60:61]
	v_add_f32_e32 v68, v68, v103
	v_add_f32_e32 v68, v68, v104
	v_pk_mul_f32 v[106:107], v[32:33], v[32:33]
	v_add_f32_e32 v68, v68, v105
	v_add_f32_e32 v68, v68, v106
	v_pk_mul_f32 v[108:109], v[62:63], v[62:63]
	v_add_f32_e32 v68, v68, v107
	v_add_f32_e32 v68, v68, v108
	v_pk_mul_f32 v[110:111], v[34:35], v[34:35]
	v_add_f32_e32 v68, v68, v109
	v_add_f32_e32 v68, v68, v110
	v_pk_mul_f32 v[112:113], v[44:45], v[44:45]
	v_add_f32_e32 v68, v68, v111
	v_add_f32_e32 v68, v68, v112
	v_pk_mul_f32 v[46:47], v[36:37], v[36:37]
	v_add_f32_e32 v68, v68, v113
	v_add_f32_e32 v46, v68, v46
	v_pk_mul_f32 v[116:117], v[40:41], v[40:41]
	v_add_f32_e32 v46, v46, v47
	v_add_f32_e32 v46, v46, v116
	v_pk_mul_f32 v[114:115], v[38:39], v[38:39]
	v_add_f32_e32 v46, v46, v117
	v_add_f32_e32 v46, v46, v114
	v_pk_mul_f32 v[120:121], v[42:43], v[42:43]
	v_add_f32_e32 v46, v46, v115
	v_add_f32_e32 v46, v46, v120
	v_pk_mul_f32 v[118:119], v[16:17], v[16:17]
	v_add_f32_e32 v46, v46, v121
	v_add_f32_e32 v46, v46, v118
	v_pk_mul_f32 v[124:125], v[26:27], v[26:27]
	v_add_f32_e32 v46, v46, v119
	v_add_f32_e32 v46, v46, v124
	v_pk_mul_f32 v[122:123], v[18:19], v[18:19]
	v_add_f32_e32 v46, v46, v125
	v_add_f32_e32 v46, v46, v122
	v_pk_mul_f32 v[88:89], v[28:29], v[28:29]
	v_add_f32_e32 v46, v46, v123
	v_add_f32_e32 v46, v46, v88
	v_pk_mul_f32 v[30:31], v[20:21], v[20:21]
	v_add_f32_e32 v46, v46, v89
	v_add_f32_e32 v30, v46, v30
	v_pk_mul_f32 v[128:129], v[24:25], v[24:25]
	v_add_f32_e32 v30, v30, v31
	v_add_f32_e32 v30, v30, v128
	v_pk_mul_f32 v[126:127], v[22:23], v[22:23]
	v_add_f32_e32 v30, v30, v129
	v_add_f32_e32 v30, v30, v126
	v_pk_mul_f32 v[132:133], v[4:5], v[4:5]
	v_add_f32_e32 v30, v30, v127
	v_add_f32_e32 v30, v30, v132
	v_pk_mul_f32 v[130:131], v[0:1], v[0:1]
	v_add_f32_e32 v30, v30, v133
	v_add_f32_e32 v30, v30, v130
	v_pk_mul_f32 v[8:9], v[6:7], v[6:7]
	v_add_f32_e32 v30, v30, v131
	v_add_f32_e32 v8, v30, v8
	v_pk_mul_f32 v[10:11], v[2:3], v[2:3]
	v_add_f32_e32 v8, v8, v9
	v_add_f32_e32 v8, v8, v10
	v_pk_mul_f32 v[70:71], v[64:65], v[64:65]
	v_add_f32_e32 v8, v8, v11
	v_add_f32_e32 v8, v8, v70
	v_pk_mul_f32 v[72:73], v[66:67], v[66:67]
	v_add_f32_e32 v8, v8, v71
	v_add_f32_e32 v8, v8, v72
	v_add_f32_e32 v10, v8, v73
	ds_bpermute_b32 v11, v171, v10
	global_load_dwordx4 v[122:125], v69, s[10:11] offset:32
	global_load_dwordx4 v[126:129], v69, s[10:11] offset:64
	global_load_dwordx4 v[130:133], v69, s[10:11] offset:96
	global_load_dwordx4 v[134:137], v69, s[10:11] offset:128
	global_load_dwordx4 v[138:141], v69, s[10:11] offset:160
	global_load_dwordx4 v[142:145], v69, s[10:11] offset:192
	global_load_dwordx4 v[146:149], v69, s[10:11] offset:224
	global_load_dwordx4 v[150:153], v69, s[10:11] offset:256
	global_load_dwordx4 v[180:183], v69, s[10:11] offset:288
	global_load_dwordx4 v[184:187], v69, s[10:11] offset:320
	global_load_dwordx4 v[188:191], v69, s[10:11] offset:352
	global_load_dwordx4 v[192:195], v69, s[10:11] offset:384
	global_load_dwordx4 v[196:199], v69, s[10:11] offset:416
	global_load_dwordx4 v[200:203], v69, s[10:11] offset:448
	global_load_dwordx4 v[216:219], v69, s[10:11] offset:480
	v_readlane_b32 s0, v255, 57
	v_ashrrev_i32_e32 v177, 31, v176
	v_readlane_b32 s1, v255, 58
	s_lshl_b32 s24, s36, 1
	s_waitcnt lgkmcnt(0)
	v_add_f32_e32 v10, v10, v11
	v_fmamk_f32 v10, v10, 0x3c000000, v248
	v_mul_f32_e32 v11, 0x4b800000, v10
	v_cmp_gt_f32_e32 vcc, s82, v10
	v_lshl_add_u64 v[74:75], v[176:177], 0, s[0:1]
	v_and_or_b32 v74, v179, 31, v74
	v_cndmask_b32_e32 v10, v10, v11, vcc
	v_rsq_f32_e32 v10, v10
	v_lshlrev_b64 v[8:9], 11, v[74:75]
	v_lshl_add_u64 v[8:9], s[92:93], 0, v[8:9]
	v_lshl_add_u64 v[8:9], v[8:9], 0, s[24:25]
	v_lshlrev_b32_e32 v96, 1, v96
	v_lshl_add_u64 v[30:31], v[8:9], 0, v[96:97]
	v_mul_f32_e32 v8, 0x45800000, v10
	v_cndmask_b32_e32 v8, v10, v8, vcc
	v_mul_f32_e32 v46, 0x3f4ccccd, v8
	v_pk_mul_f32 v[8:9], v[76:77], v[46:47] op_sel_hi:[1,0]
	v_pk_mul_f32 v[10:11], v[50:51], v[46:47] op_sel_hi:[1,0]
	s_waitcnt vmcnt(0)
	v_pk_mul_f32 v[8:9], v[12:13], v[8:9]
	v_pk_mul_f32 v[10:11], v[14:15], v[10:11]
	v_cvt_pk_bf16_f32 v8, v8, v9
	v_cvt_pk_bf16_f32 v9, v10, v11
	v_add_co_u32_e32 v10, vcc, s33, v30
	v_pk_mul_f32 v[14:15], v[80:81], v[46:47] op_sel_hi:[1,0]
	s_nop 0
	v_addc_co_u32_e32 v11, vcc, 0, v31, vcc
	global_store_dwordx2 v[10:11], v[8:9], off offset:1024
	s_mov_b64 s[0:1], 0x11d00400
	v_lshl_add_u64 v[12:13], v[30:31], 0, s[0:1]
	v_pk_mul_f32 v[30:31], v[52:53], v[46:47] op_sel_hi:[1,0]
	v_pk_mul_f32 v[16:17], v[16:17], v[46:47] op_sel_hi:[1,0]
	v_pk_mul_f32 v[4:5], v[4:5], v[46:47] op_sel_hi:[1,0]
	v_pk_mul_f32 v[0:1], v[0:1], v[46:47] op_sel_hi:[1,0]
	v_pk_mul_f32 v[2:3], v[2:3], v[46:47] op_sel_hi:[1,0]
	v_readlane_b32 s5, v255, 27
	v_readlane_b32 s6, v255, 28
	s_mov_b32 s6, s78
	s_mov_b32 s5, s72
	v_readlane_b32 s7, v255, 29
	v_readlane_b32 s8, v255, 30
	v_readlane_b32 s9, v255, 31
	v_readlane_b32 s12, v255, 34
	v_readlane_b32 s13, v255, 35
	v_readlane_b32 s14, v255, 36
	v_readlane_b32 s15, v255, 37
	v_readlane_b32 s16, v255, 38
	v_readlane_b32 s17, v255, 39
	v_readlane_b32 s18, v255, 40
	v_readlane_b32 s19, v255, 41
	v_pk_mul_f32 v[122:123], v[122:123], v[14:15]
	v_pk_mul_f32 v[14:15], v[48:49], v[46:47] op_sel_hi:[1,0]
	v_cvt_pk_bf16_f32 v122, v122, v123
	v_pk_mul_f32 v[124:125], v[124:125], v[14:15]
	v_pk_mul_f32 v[14:15], v[82:83], v[46:47] op_sel_hi:[1,0]
	v_cvt_pk_bf16_f32 v123, v124, v125
	global_store_dwordx2 v[12:13], v[122:123], off offset:16
	v_pk_mul_f32 v[126:127], v[126:127], v[14:15]
	v_pk_mul_f32 v[128:129], v[128:129], v[30:31]
	v_cvt_pk_bf16_f32 v126, v126, v127
	v_cvt_pk_bf16_f32 v127, v128, v129
	global_store_dwordx2 v[12:13], v[126:127], off offset:32
	v_pk_mul_f32 v[14:15], v[84:85], v[46:47] op_sel_hi:[1,0]
	v_pk_mul_f32 v[30:31], v[54:55], v[46:47] op_sel_hi:[1,0]
	v_pk_mul_f32 v[130:131], v[14:15], v[130:131]
	v_pk_mul_f32 v[132:133], v[30:31], v[132:133]
	v_cvt_pk_bf16_f32 v130, v130, v131
	v_cvt_pk_bf16_f32 v131, v132, v133
	global_store_dwordx2 v[12:13], v[130:131], off offset:48
	v_pk_mul_f32 v[14:15], v[58:59], v[46:47] op_sel_hi:[1,0]
	v_pk_mul_f32 v[30:31], v[56:57], v[46:47] op_sel_hi:[1,0]
	v_pk_mul_f32 v[134:135], v[14:15], v[134:135]
	v_pk_mul_f32 v[136:137], v[30:31], v[136:137]
	v_cvt_pk_bf16_f32 v134, v134, v135
	v_cvt_pk_bf16_f32 v135, v136, v137
	global_store_dwordx2 v[12:13], v[134:135], off offset:64
	v_pk_mul_f32 v[14:15], v[60:61], v[46:47] op_sel_hi:[1,0]
	v_pk_mul_f32 v[30:31], v[32:33], v[46:47] op_sel_hi:[1,0]
	v_pk_mul_f32 v[138:139], v[14:15], v[138:139]
	v_pk_mul_f32 v[140:141], v[30:31], v[140:141]
	v_cvt_pk_bf16_f32 v138, v138, v139
	v_cvt_pk_bf16_f32 v139, v140, v141
	global_store_dwordx2 v[12:13], v[138:139], off offset:80
	v_pk_mul_f32 v[14:15], v[62:63], v[46:47] op_sel_hi:[1,0]
	v_pk_mul_f32 v[30:31], v[34:35], v[46:47] op_sel_hi:[1,0]
	v_pk_mul_f32 v[142:143], v[14:15], v[142:143]
	v_pk_mul_f32 v[144:145], v[30:31], v[144:145]
	v_cvt_pk_bf16_f32 v142, v142, v143
	v_cvt_pk_bf16_f32 v143, v144, v145
	global_store_dwordx2 v[12:13], v[142:143], off offset:96
	v_pk_mul_f32 v[14:15], v[44:45], v[46:47] op_sel_hi:[1,0]
	v_pk_mul_f32 v[30:31], v[36:37], v[46:47] op_sel_hi:[1,0]
	v_pk_mul_f32 v[146:147], v[14:15], v[146:147]
	v_pk_mul_f32 v[148:149], v[30:31], v[148:149]
	v_cvt_pk_bf16_f32 v146, v146, v147
	v_cvt_pk_bf16_f32 v147, v148, v149
	global_store_dwordx2 v[12:13], v[146:147], off offset:112
	v_pk_mul_f32 v[14:15], v[40:41], v[46:47] op_sel_hi:[1,0]
	v_pk_mul_f32 v[30:31], v[38:39], v[46:47] op_sel_hi:[1,0]
	v_pk_mul_f32 v[150:151], v[14:15], v[150:151]
	v_pk_mul_f32 v[152:153], v[30:31], v[152:153]
	v_cvt_pk_bf16_f32 v150, v150, v151
	v_cvt_pk_bf16_f32 v151, v152, v153
	global_store_dwordx2 v[12:13], v[150:151], off offset:128
	v_pk_mul_f32 v[14:15], v[42:43], v[46:47] op_sel_hi:[1,0]
	v_pk_mul_f32 v[182:183], v[16:17], v[182:183]
	v_pk_mul_f32 v[180:181], v[14:15], v[180:181]
	v_pk_mul_f32 v[14:15], v[26:27], v[46:47] op_sel_hi:[1,0]
	v_cvt_pk_bf16_f32 v180, v180, v181
	v_cvt_pk_bf16_f32 v181, v182, v183
	global_store_dwordx2 v[12:13], v[180:181], off offset:144
	v_pk_mul_f32 v[16:17], v[18:19], v[46:47] op_sel_hi:[1,0]
	v_pk_mul_f32 v[184:185], v[14:15], v[184:185]
	v_pk_mul_f32 v[186:187], v[16:17], v[186:187]
	v_cvt_pk_bf16_f32 v184, v184, v185
	v_cvt_pk_bf16_f32 v185, v186, v187
	global_store_dwordx2 v[12:13], v[184:185], off offset:160
	v_pk_mul_f32 v[14:15], v[28:29], v[46:47] op_sel_hi:[1,0]
	v_pk_mul_f32 v[16:17], v[20:21], v[46:47] op_sel_hi:[1,0]
	v_pk_mul_f32 v[188:189], v[14:15], v[188:189]
	v_pk_mul_f32 v[190:191], v[16:17], v[190:191]
	v_cvt_pk_bf16_f32 v188, v188, v189
	v_cvt_pk_bf16_f32 v189, v190, v191
	global_store_dwordx2 v[12:13], v[188:189], off offset:176
	v_pk_mul_f32 v[14:15], v[24:25], v[46:47] op_sel_hi:[1,0]
	v_pk_mul_f32 v[16:17], v[22:23], v[46:47] op_sel_hi:[1,0]
	v_pk_mul_f32 v[192:193], v[14:15], v[192:193]
	v_pk_mul_f32 v[194:195], v[16:17], v[194:195]
	v_cvt_pk_bf16_f32 v192, v192, v193
	v_cvt_pk_bf16_f32 v193, v194, v195
	global_store_dwordx2 v[12:13], v[192:193], off offset:192
	v_pk_mul_f32 v[4:5], v[4:5], v[196:197]
	v_pk_mul_f32 v[0:1], v[0:1], v[198:199]
	v_cvt_pk_bf16_f32 v4, v4, v5
	v_cvt_pk_bf16_f32 v5, v0, v1
	global_store_dwordx2 v[12:13], v[4:5], off offset:208
	v_pk_mul_f32 v[0:1], v[6:7], v[46:47] op_sel_hi:[1,0]
	v_pk_mul_f32 v[4:5], v[64:65], v[46:47] op_sel_hi:[1,0]
	v_pk_mul_f32 v[6:7], v[66:67], v[46:47] op_sel_hi:[1,0]
	v_pk_mul_f32 v[0:1], v[0:1], v[200:201]
	v_pk_mul_f32 v[2:3], v[2:3], v[202:203]
	v_cvt_pk_bf16_f32 v0, v0, v1
	v_cvt_pk_bf16_f32 v1, v2, v3
	global_store_dwordx2 v[12:13], v[0:1], off offset:224
	v_pk_mul_f32 v[216:217], v[4:5], v[216:217]
	v_pk_mul_f32 v[218:219], v[6:7], v[218:219]
	v_cvt_pk_bf16_f32 v216, v216, v217
	v_cvt_pk_bf16_f32 v217, v218, v219
	global_store_dwordx2 v[12:13], v[216:217], off offset:240
